# sample-row LayerNorm rows moved to workgroups 192-255 (off the critical path of the following GEMM)
# baseline (speedup 1.0000x reference)
.LBB0_2320:
	s_or_b32 s4, s60, 6
	s_load_dword s5, s[0:1], 0xc8
	s_waitcnt lgkmcnt(0)
	s_cmp_gt_i32 s5, s4
	s_cbranch_scc1 .LBB0_2382
	s_load_dword s5, s[0:1], 0xcc
	s_waitcnt lgkmcnt(0)
	s_cmp_ge_i32 s4, s5
	s_cbranch_scc1 .LBB0_2382
	v_mbcnt_lo_u32_b32 v0, -1, 0
	v_mbcnt_hi_u32_b32 v0, -1, v0
	s_mov_b32 s4, s80
	s_load_dwordx2 s[6:7], s[0:1], 0xc0
	s_waitcnt lgkmcnt(0)
	s_lshl_b32 s4, s4, 3
	s_load_dword s9, s[0:1], 0xd4
	s_waitcnt lgkmcnt(0)
	s_add_i32 s8, s4, s33
	s_load_dwordx2 s[4:5], s[0:1], 0x80
	s_waitcnt lgkmcnt(0)
	s_cmpk_eq_i32 s9, 0x100
	s_cselect_b32 s12, 0x4000, 0
	s_load_dwordx2 s[14:15], s[0:1], 0x88
	s_waitcnt lgkmcnt(0)
	s_add_i32 s8, s8, s12
	s_cmpk_eq_i32 s9, 0x100
	s_cbranch_scc0 ln1_norm
	s_sub_i32 s8, s8, 0x600
	s_cmpk_lt_i32 s8, 0x4000
	s_cbranch_scc1 .LBB0_2325
ln1_norm:
	s_cmpk_lt_i32 s8, 0x4200
	s_cbranch_scc0 .LBB0_2325
	v_and_b32_e32 v2, 64, v245
	v_add_u32_e32 v2, 64, v2
	v_xor_b32_e32 v3, 1, v245
	v_cmp_lt_i32_e32 vcc, v3, v2
	v_readlane_b32 s16, v255, 10
	v_readlane_b32 s17, v255, 11
	v_cndmask_b32_e32 v3, v245, v3, vcc
	v_lshlrev_b32_e32 v16, 2, v3
	v_xor_b32_e32 v3, 2, v245
	v_cmp_lt_i32_e32 vcc, v3, v2
	s_lshl_b32 s48, s16, 10
	s_lshl_b32 s12, s9, 3
	v_cndmask_b32_e32 v3, v245, v3, vcc
	v_lshlrev_b32_e32 v28, 2, v3
	v_xor_b32_e32 v3, 4, v245
	v_cmp_lt_i32_e32 vcc, v3, v2
	s_lshl_b64 s[16:17], s[48:49], 2
	s_add_u32 s14, s14, s16
	v_cndmask_b32_e32 v3, v245, v3, vcc
	v_lshlrev_b32_e32 v29, 2, v3
	v_xor_b32_e32 v3, 8, v245
	v_cmp_lt_i32_e32 vcc, v3, v2
	s_addc_u32 s15, s15, s17
	v_lshlrev_b32_e32 v0, 2, v0
	v_cndmask_b32_e32 v3, v245, v3, vcc
	v_lshlrev_b32_e32 v30, 2, v3
	v_xor_b32_e32 v3, 16, v245
	v_cmp_lt_i32_e32 vcc, v3, v2
	s_add_u32 s4, s4, s16
	v_ashrrev_i32_e32 v1, 31, v0
	v_cndmask_b32_e32 v3, v245, v3, vcc
	v_lshlrev_b32_e32 v31, 2, v3
	v_xor_b32_e32 v3, 32, v245
	v_cmp_lt_i32_e32 vcc, v3, v2
	s_addc_u32 s5, s5, s17
	s_ashr_i32 s9, s8, 31
	v_cndmask_b32_e32 v2, v245, v3, vcc
	v_lshlrev_b32_e32 v32, 2, v2
	v_lshlrev_b64 v[2:3], 2, v[0:1]
	v_lshl_add_u64 v[12:13], s[4:5], 0, v[2:3]
	s_lshl_b64 s[4:5], s[8:9], 11
	v_lshl_add_u64 v[18:19], v[0:1], 1, s[4:5]
	s_ashr_i32 s13, s12, 31
	s_lshl_b64 s[4:5], s[8:9], 12
	v_lshl_add_u64 v[14:15], s[14:15], 0, v[2:3]
	s_lshl_b64 s[14:15], s[12:13], 11
	v_lshl_add_u64 v[20:21], s[4:5], 0, v[2:3]
	s_lshl_b64 s[16:17], s[12:13], 12

.LBB0_2712:
	s_lshl_b32 s12, s12, 3
	s_add_i32 s12, s12, s33
	s_cmpk_eq_i32 s13, 0x100
	s_cselect_b32 s14, 0x4000, 0
	s_add_i32 s12, s12, s14
	s_cmpk_eq_i32 s13, 0x100
	s_cbranch_scc0 ln2_norm
	s_sub_i32 s12, s12, 0x600
	s_cmpk_lt_i32 s12, 0x4000
	s_cbranch_scc1 .LBB0_2731
ln2_norm:
	s_cmpk_gt_i32 s12, 0x41ff
	s_cbranch_scc1 .LBB0_2731
	v_lshlrev_b32_e32 v26, 2, v0
	v_and_b32_e32 v0, 64, v245
	v_add_u32_e32 v0, 64, v0
	v_xor_b32_e32 v1, 1, v245
	v_cmp_lt_i32_e32 vcc, v1, v0
	v_readlane_b32 s14, v255, 4
	v_readlane_b32 s16, v255, 10
	v_cndmask_b32_e32 v1, v245, v1, vcc
	v_lshlrev_b32_e32 v16, 2, v1
	v_xor_b32_e32 v1, 2, v245
	v_cmp_lt_i32_e32 vcc, v1, v0
	v_readlane_b32 s15, v255, 5
	s_lshl_b32 s48, s16, 10
	v_cndmask_b32_e32 v1, v245, v1, vcc
	v_lshlrev_b32_e32 v44, 2, v1
	v_xor_b32_e32 v1, 4, v245
	v_cmp_lt_i32_e32 vcc, v1, v0
	s_xor_b64 s[14:15], s[14:15], -1
	s_lshl_b32 s16, s13, 3
	v_cndmask_b32_e32 v1, v245, v1, vcc
	v_lshlrev_b32_e32 v45, 2, v1
	v_xor_b32_e32 v1, 8, v245
	v_cmp_lt_i32_e32 vcc, v1, v0
	s_lshl_b64 s[20:21], s[48:49], 2
	s_add_u32 s22, s18, s20
	v_cndmask_b32_e32 v1, v245, v1, vcc
	v_lshlrev_b32_e32 v46, 2, v1
	v_xor_b32_e32 v1, 16, v245
	v_cmp_lt_i32_e32 vcc, v1, v0
	s_addc_u32 s23, s19, s21
	s_add_u32 s6, s6, s20
	v_cndmask_b32_e32 v1, v245, v1, vcc
	v_lshlrev_b32_e32 v47, 2, v1
	v_xor_b32_e32 v1, 32, v245
	s_addc_u32 s7, s7, s21
	v_cmp_lt_i32_e32 vcc, v1, v0
	v_readlane_b32 s17, v255, 11
	s_cmp_eq_u64 s[4:5], 0
	v_ashrrev_i32_e32 v27, 31, v26
	v_cndmask_b32_e32 v0, v245, v1, vcc
	s_cselect_b64 s[18:19], -1, 0
	v_lshlrev_b32_e32 v48, 2, v0
	v_lshlrev_b64 v[0:1], 2, v[26:27]
	s_ashr_i32 s13, s12, 31
	s_ashr_i32 s17, s16, 31
	v_lshl_add_u64 v[30:31], s[6:7], 0, v[0:1]
	s_lshl_b64 s[6:7], s[12:13], 12
	s_lshl_b64 s[20:21], s[16:17], 12
	s_add_u32 s26, s4, s6
	s_addc_u32 s27, s5, s7
	s_lshl_b64 s[4:5], s[12:13], 11
	v_lshl_add_u64 v[28:29], s[22:23], 0, v[0:1]
	v_lshl_add_u64 v[32:33], s[6:7], 0, v[0:1]
	v_lshl_add_u64 v[34:35], v[26:27], 1, s[4:5]
	s_lshl_b64 s[22:23], s[16:17], 11
	s_branch .LBB0_2715
